# hand-written SWIGLU epilogue: batched stats loads, permlane16_swap + dwordx4 stores (half the store instructions)
# speedup vs baseline: 1.0204x; 1.0146x over previous
; DI unsigned pk2(float lo, float hi) { const f32x2v v = {lo, hi}; const bf16x2v b = __builtin_convertvector(v, bf16x2v); return __builtin_bit_cast(unsigned, b); }
; DI float siluf_(float x) { return x * sigmoidf_(x); }
; DI float rs_of(float ss, float inv_n) { return __builtin_amdgcn_rsqf(ss * inv_n + EPS); }
; DI float sum16_fq(const float* p, int fq) { const f32x4 a = *(const f32x4*)(p + 4 * fq); float s = (a[0] + a[1]) + (a[2] + a[3]); s += __shfl_xor(s, 16); s += __shfl_xor(s, 32); return s; }
; DI void epilogue(int kind, int l, const f32x4 (&acc)[2][2][4][2], const Unit& u, int wr, int wc, int fr, int fq) {
;     ...
;     if (E.mode == EM_SWIGLU) {
; #pragma unroll
;         for (int ai = 0; ai < 2; ++ai)
; #pragma unroll
;             for (int m = 0; m < 4; ++m) { const int row = row0 + ai * HALF + m * 16; const float rs = rs_of(sum16_fq(E.ss_in + (size_t)row * 16, fq), 1.f / 1024.f);
; #pragma unroll
;                 for (int bj = 0; bj < 2; ++bj) { const f32x4 g = acc[ai][bj][m][0] * rs, up = acc[ai][bj][m][1] * rs;
;                     u32x2 w; w.x = pk2(siluf_(g[0]) * up[0], siluf_(g[1]) * up[1]); w.y = pk2(siluf_(g[2]) * up[2], siluf_(g[3]) * up[3]);
;                     *(u32x2*)(E.o0 + (size_t)row * FF + ((col0 + bj * HALF) >> 1)) = w; } }
.LBB0_812:
	v_lshlrev_b32_e32 v24, 2, v166
	s_waitcnt lgkmcnt(0)
	v_lshl_add_u64 v[250:251], s[88:89], 0, v[24:25]
	v_ashrrev_i32_e32 v173, 31, v172
	v_lshlrev_b64 v[130:131], 6, v[172:173]
	v_lshl_add_u64 v[250:251], v[250:251], 0, v[130:131]
	v_mov_b32_e32 v252, 0x2000
	v_mov_b32_e32 v253, 0
	v_lshl_add_u64 v[252:253], v[250:251], 0, v[252:253]
	global_load_dwordx4 v[216:219], v[250:251], off
	global_load_dwordx4 v[220:223], v[250:251], off offset:1024
	global_load_dwordx4 v[224:227], v[250:251], off offset:2048
	global_load_dwordx4 v[228:231], v[250:251], off offset:3072
	global_load_dwordx4 v[232:235], v[252:253], off
	global_load_dwordx4 v[236:239], v[252:253], off offset:1024
	global_load_dwordx4 v[240:243], v[252:253], off offset:2048
	global_load_dwordx4 v[244:247], v[252:253], off offset:3072
	v_xor_b32_e32 v248, 16, v187
	v_xor_b32_e32 v249, 32, v187
	v_lshlrev_b32_e32 v248, 2, v248
	v_lshlrev_b32_e32 v249, 2, v249
	s_movk_i32 s6, 0x1600
	v_mov_b64_e32 v[130:131], s[78:79]
	v_mad_i64_i32 v[150:151], s[4:5], v172, s6, v[130:131]
	v_and_b32_e32 v24, 16, v187
	v_mul_u32_u24_e32 v24, 0x78, v24
	v_lshrrev_b32_e32 v24, 4, v24
	v_add_u32_e32 v132, v174, v24
	v_ashrrev_i32_e32 v133, 31, v132
	v_lshl_add_u64 v[150:151], v[132:133], 0, v[150:151]
	s_waitcnt vmcnt(0)
	v_add_f32_e32 v216, v217, v216
	v_add_f32_e32 v220, v221, v220
	v_add_f32_e32 v224, v225, v224
	v_add_f32_e32 v228, v229, v228
	v_add_f32_e32 v232, v233, v232
	v_add_f32_e32 v236, v237, v236
	v_add_f32_e32 v240, v241, v240
	v_add_f32_e32 v244, v245, v244
	v_add_f32_e32 v218, v218, v219
	v_add_f32_e32 v222, v222, v223
	v_add_f32_e32 v226, v226, v227
	v_add_f32_e32 v230, v230, v231
	v_add_f32_e32 v234, v234, v235
	v_add_f32_e32 v238, v238, v239
	v_add_f32_e32 v242, v242, v243
	v_add_f32_e32 v246, v246, v247
	v_add_f32_e32 v216, v216, v218
	v_add_f32_e32 v220, v220, v222
	v_add_f32_e32 v224, v224, v226
	v_add_f32_e32 v228, v228, v230
	v_add_f32_e32 v232, v232, v234
	v_add_f32_e32 v236, v236, v238
	v_add_f32_e32 v240, v240, v242
	v_add_f32_e32 v244, v244, v246
	ds_bpermute_b32 v217, v248, v216
	ds_bpermute_b32 v221, v248, v220
	ds_bpermute_b32 v225, v248, v224
	ds_bpermute_b32 v229, v248, v228
	ds_bpermute_b32 v233, v248, v232
	ds_bpermute_b32 v237, v248, v236
	ds_bpermute_b32 v241, v248, v240
	ds_bpermute_b32 v245, v248, v244
	s_waitcnt lgkmcnt(0)
	v_add_f32_e32 v216, v216, v217
	v_add_f32_e32 v220, v220, v221
	v_add_f32_e32 v224, v224, v225
	v_add_f32_e32 v228, v228, v229
	v_add_f32_e32 v232, v232, v233
	v_add_f32_e32 v236, v236, v237
	v_add_f32_e32 v240, v240, v241
	v_add_f32_e32 v244, v244, v245
	ds_bpermute_b32 v217, v249, v216
	ds_bpermute_b32 v221, v249, v220
	ds_bpermute_b32 v225, v249, v224
	ds_bpermute_b32 v229, v249, v228
	ds_bpermute_b32 v233, v249, v232
	ds_bpermute_b32 v237, v249, v236
	ds_bpermute_b32 v241, v249, v240
	ds_bpermute_b32 v245, v249, v244
	s_waitcnt lgkmcnt(0)
	v_add_f32_e32 v216, v216, v217
	v_add_f32_e32 v220, v220, v221
	v_add_f32_e32 v224, v224, v225
	v_add_f32_e32 v228, v228, v229
	v_add_f32_e32 v232, v232, v233
	v_add_f32_e32 v236, v236, v237
	v_add_f32_e32 v240, v240, v241
	v_add_f32_e32 v244, v244, v245
	v_fmamk_f32 v216, v216, 0x3a800000, v185
	v_fmamk_f32 v220, v220, 0x3a800000, v185
	v_fmamk_f32 v224, v224, 0x3a800000, v185
	v_fmamk_f32 v228, v228, 0x3a800000, v185
	v_fmamk_f32 v232, v232, 0x3a800000, v185
	v_fmamk_f32 v236, v236, 0x3a800000, v185
	v_fmamk_f32 v240, v240, 0x3a800000, v185
	v_fmamk_f32 v244, v244, 0x3a800000, v185
	v_rsq_f32_e32 v216, v216
	v_rsq_f32_e32 v220, v220
	v_rsq_f32_e32 v224, v224
	v_rsq_f32_e32 v228, v228
	v_rsq_f32_e32 v232, v232
	v_rsq_f32_e32 v236, v236
	v_rsq_f32_e32 v240, v240
	v_rsq_f32_e32 v244, v244
	v_mul_f32_e32 v217, 0xbfb8aa3b, v216
	v_mul_f32_e32 v221, 0xbfb8aa3b, v220
	v_mul_f32_e32 v225, 0xbfb8aa3b, v224
	v_mul_f32_e32 v229, 0xbfb8aa3b, v228
	v_mul_f32_e32 v233, 0xbfb8aa3b, v232
	v_mul_f32_e32 v237, 0xbfb8aa3b, v236
	v_mul_f32_e32 v241, 0xbfb8aa3b, v240
	v_mul_f32_e32 v245, 0xbfb8aa3b, v244
	v_mul_f32_e32 v218, v216, v216
	v_mul_f32_e32 v222, v220, v220
	v_mul_f32_e32 v226, v224, v224
	v_mul_f32_e32 v230, v228, v228
	v_mul_f32_e32 v234, v232, v232
	v_mul_f32_e32 v238, v236, v236
	v_mul_f32_e32 v242, v240, v240
	v_mul_f32_e32 v246, v244, v244
	v_mul_f32_e32 v130, v126, v217
	v_mul_f32_e32 v131, v127, v217
	v_mul_f32_e32 v132, v128, v217
	v_mul_f32_e32 v133, v129, v217
	v_exp_f32_e32 v130, v130
	v_exp_f32_e32 v131, v131
	v_exp_f32_e32 v132, v132
	v_exp_f32_e32 v133, v133
	v_pk_mul_f32 v[134:135], v[126:127], v[122:123]
	v_pk_mul_f32 v[136:137], v[128:129], v[124:125]
	v_add_f32_e32 v130, 1.0, v130
	v_add_f32_e32 v131, 1.0, v131
	v_add_f32_e32 v132, 1.0, v132
	v_add_f32_e32 v133, 1.0, v133
	v_rcp_f32_e32 v130, v130
	v_rcp_f32_e32 v131, v131
	v_rcp_f32_e32 v132, v132
	v_rcp_f32_e32 v133, v133
	v_pk_mul_f32 v[130:131], v[130:131], v[218:219] op_sel_hi:[1,0]
	v_pk_mul_f32 v[132:133], v[132:133], v[218:219] op_sel_hi:[1,0]
	v_pk_mul_f32 v[134:135], v[134:135], v[130:131]
	v_pk_mul_f32 v[136:137], v[136:137], v[132:133]
	v_cvt_pk_bf16_f32 v138, v134, v135
	v_cvt_pk_bf16_f32 v139, v136, v137
	v_mul_f32_e32 v130, v118, v217
	v_mul_f32_e32 v131, v119, v217
	v_mul_f32_e32 v132, v120, v217
	v_mul_f32_e32 v133, v121, v217
	v_exp_f32_e32 v130, v130
	v_exp_f32_e32 v131, v131
	v_exp_f32_e32 v132, v132
	v_exp_f32_e32 v133, v133
	v_pk_mul_f32 v[134:135], v[118:119], v[114:115]
	v_pk_mul_f32 v[136:137], v[120:121], v[116:117]
	v_add_f32_e32 v130, 1.0, v130
	v_add_f32_e32 v131, 1.0, v131
	v_add_f32_e32 v132, 1.0, v132
	v_add_f32_e32 v133, 1.0, v133
	v_rcp_f32_e32 v130, v130
	v_rcp_f32_e32 v131, v131
	v_rcp_f32_e32 v132, v132
; DI unsigned pk2(float lo, float hi) { const f32x2v v = {lo, hi}; const bf16x2v b = __builtin_convertvector(v, bf16x2v); return __builtin_bit_cast(unsigned, b); }
; DI float siluf_(float x) { return x * sigmoidf_(x); }
; DI float rs_of(float ss, float inv_n) { return __builtin_amdgcn_rsqf(ss * inv_n + EPS); }
; DI float sum16_fq(const float* p, int fq) { const f32x4 a = *(const f32x4*)(p + 4 * fq); float s = (a[0] + a[1]) + (a[2] + a[3]); s += __shfl_xor(s, 16); s += __shfl_xor(s, 32); return s; }
; DI void epilogue(int kind, int l, const f32x4 (&acc)[2][2][4][2], const Unit& u, int wr, int wc, int fr, int fq) {
;     ...
;             for (int m = 0; m < 4; ++m) { const int row = row0 + ai * HALF + m * 16; const float rs = rs_of(sum16_fq(E.ss_in + (size_t)row * 16, fq), 1.f / 1024.f);
; #pragma unroll
;                 for (int bj = 0; bj < 2; ++bj) { const f32x4 g = acc[ai][bj][m][0] * rs, up = acc[ai][bj][m][1] * rs;
;                     u32x2 w; w.x = pk2(siluf_(g[0]) * up[0], siluf_(g[1]) * up[1]); w.y = pk2(siluf_(g[2]) * up[2], siluf_(g[3]) * up[3]);
;                     *(u32x2*)(E.o0 + (size_t)row * FF + ((col0 + bj * HALF) >> 1)) = w; } }
	v_rcp_f32_e32 v133, v133
	v_pk_mul_f32 v[130:131], v[130:131], v[218:219] op_sel_hi:[1,0]
	v_pk_mul_f32 v[132:133], v[132:133], v[218:219] op_sel_hi:[1,0]
	v_pk_mul_f32 v[134:135], v[134:135], v[130:131]
	v_pk_mul_f32 v[136:137], v[136:137], v[132:133]
	v_cvt_pk_bf16_f32 v140, v134, v135
	v_cvt_pk_bf16_f32 v141, v136, v137
	s_nop 1
	v_permlane16_swap_b32_e32 v138, v140
	v_permlane16_swap_b32_e32 v139, v141
	global_store_dwordx4 v[150:151], v[138:141], off
	v_add_co_u32_e32 v150, vcc, 0x16000, v150
	s_nop 1
	v_addc_co_u32_e32 v151, vcc, 0, v151, vcc
	v_mul_f32_e32 v130, v110, v221
	v_mul_f32_e32 v131, v111, v221
	v_mul_f32_e32 v132, v112, v221
	v_mul_f32_e32 v133, v113, v221
	v_exp_f32_e32 v130, v130
	v_exp_f32_e32 v131, v131
	v_exp_f32_e32 v132, v132
	v_exp_f32_e32 v133, v133
	v_pk_mul_f32 v[134:135], v[110:111], v[106:107]
	v_pk_mul_f32 v[136:137], v[112:113], v[108:109]
	v_add_f32_e32 v130, 1.0, v130
	v_add_f32_e32 v131, 1.0, v131
	v_add_f32_e32 v132, 1.0, v132
	v_add_f32_e32 v133, 1.0, v133
	v_rcp_f32_e32 v130, v130
	v_rcp_f32_e32 v131, v131
	v_rcp_f32_e32 v132, v132
	v_rcp_f32_e32 v133, v133
	v_pk_mul_f32 v[130:131], v[130:131], v[222:223] op_sel_hi:[1,0]
	v_pk_mul_f32 v[132:133], v[132:133], v[222:223] op_sel_hi:[1,0]
	v_pk_mul_f32 v[134:135], v[134:135], v[130:131]
	v_pk_mul_f32 v[136:137], v[136:137], v[132:133]
	v_cvt_pk_bf16_f32 v142, v134, v135
	v_cvt_pk_bf16_f32 v143, v136, v137
	v_mul_f32_e32 v130, v102, v221
	v_mul_f32_e32 v131, v103, v221
	v_mul_f32_e32 v132, v104, v221
	v_mul_f32_e32 v133, v105, v221
	v_exp_f32_e32 v130, v130
	v_exp_f32_e32 v131, v131
	v_exp_f32_e32 v132, v132
	v_exp_f32_e32 v133, v133
	v_pk_mul_f32 v[134:135], v[102:103], v[98:99]
	v_pk_mul_f32 v[136:137], v[104:105], v[100:101]
	v_add_f32_e32 v130, 1.0, v130
	v_add_f32_e32 v131, 1.0, v131
	v_add_f32_e32 v132, 1.0, v132
	v_add_f32_e32 v133, 1.0, v133
	v_rcp_f32_e32 v130, v130
	v_rcp_f32_e32 v131, v131
	v_rcp_f32_e32 v132, v132
	v_rcp_f32_e32 v133, v133
	v_pk_mul_f32 v[130:131], v[130:131], v[222:223] op_sel_hi:[1,0]
	v_pk_mul_f32 v[132:133], v[132:133], v[222:223] op_sel_hi:[1,0]
	v_pk_mul_f32 v[134:135], v[134:135], v[130:131]
	v_pk_mul_f32 v[136:137], v[136:137], v[132:133]
	v_cvt_pk_bf16_f32 v144, v134, v135
	v_cvt_pk_bf16_f32 v145, v136, v137
	s_nop 1
	v_permlane16_swap_b32_e32 v142, v144
	v_permlane16_swap_b32_e32 v143, v145
	global_store_dwordx4 v[150:151], v[142:145], off
	v_add_co_u32_e32 v150, vcc, 0x16000, v150
	s_nop 1
	v_addc_co_u32_e32 v151, vcc, 0, v151, vcc
	v_mul_f32_e32 v130, v94, v225
	v_mul_f32_e32 v131, v95, v225
	v_mul_f32_e32 v132, v96, v225
	v_mul_f32_e32 v133, v97, v225
	v_exp_f32_e32 v130, v130
	v_exp_f32_e32 v131, v131
	v_exp_f32_e32 v132, v132
	v_exp_f32_e32 v133, v133
	v_pk_mul_f32 v[134:135], v[94:95], v[90:91]
	v_pk_mul_f32 v[136:137], v[96:97], v[92:93]
	v_add_f32_e32 v130, 1.0, v130
	v_add_f32_e32 v131, 1.0, v131
	v_add_f32_e32 v132, 1.0, v132
	v_add_f32_e32 v133, 1.0, v133
	v_rcp_f32_e32 v130, v130
	v_rcp_f32_e32 v131, v131
	v_rcp_f32_e32 v132, v132
	v_rcp_f32_e32 v133, v133
	v_pk_mul_f32 v[130:131], v[130:131], v[226:227] op_sel_hi:[1,0]
	v_pk_mul_f32 v[132:133], v[132:133], v[226:227] op_sel_hi:[1,0]
	v_pk_mul_f32 v[134:135], v[134:135], v[130:131]
	v_pk_mul_f32 v[136:137], v[136:137], v[132:133]
	v_cvt_pk_bf16_f32 v138, v134, v135
	v_cvt_pk_bf16_f32 v139, v136, v137
	v_mul_f32_e32 v130, v86, v225
	v_mul_f32_e32 v131, v87, v225
	v_mul_f32_e32 v132, v88, v225
	v_mul_f32_e32 v133, v89, v225
	v_exp_f32_e32 v130, v130
	v_exp_f32_e32 v131, v131
	v_exp_f32_e32 v132, v132
	v_exp_f32_e32 v133, v133
	v_pk_mul_f32 v[134:135], v[86:87], v[82:83]
	v_pk_mul_f32 v[136:137], v[88:89], v[84:85]
	v_add_f32_e32 v130, 1.0, v130
	v_add_f32_e32 v131, 1.0, v131
	v_add_f32_e32 v132, 1.0, v132
	v_add_f32_e32 v133, 1.0, v133
	v_rcp_f32_e32 v130, v130
	v_rcp_f32_e32 v131, v131
	v_rcp_f32_e32 v132, v132
	v_rcp_f32_e32 v133, v133
	v_pk_mul_f32 v[130:131], v[130:131], v[226:227] op_sel_hi:[1,0]
	v_pk_mul_f32 v[132:133], v[132:133], v[226:227] op_sel_hi:[1,0]
	v_pk_mul_f32 v[134:135], v[134:135], v[130:131]
	v_pk_mul_f32 v[136:137], v[136:137], v[132:133]
	v_cvt_pk_bf16_f32 v140, v134, v135
	v_cvt_pk_bf16_f32 v141, v136, v137
	s_nop 1
	v_permlane16_swap_b32_e32 v138, v140
	v_permlane16_swap_b32_e32 v139, v141
	global_store_dwordx4 v[150:151], v[138:141], off
	v_add_co_u32_e32 v150, vcc, 0x16000, v150
	s_nop 1
	v_addc_co_u32_e32 v151, vcc, 0, v151, vcc
	v_mul_f32_e32 v130, v78, v229
	v_mul_f32_e32 v131, v79, v229
	v_mul_f32_e32 v132, v80, v229
	v_mul_f32_e32 v133, v81, v229
	v_exp_f32_e32 v130, v130
	v_exp_f32_e32 v131, v131
	v_exp_f32_e32 v132, v132
	v_exp_f32_e32 v133, v133
	v_pk_mul_f32 v[134:135], v[78:79], v[74:75]
	v_pk_mul_f32 v[136:137], v[80:81], v[76:77]
	v_add_f32_e32 v130, 1.0, v130
	v_add_f32_e32 v131, 1.0, v131
	v_add_f32_e32 v132, 1.0, v132
	v_add_f32_e32 v133, 1.0, v133
	v_rcp_f32_e32 v130, v130
	v_rcp_f32_e32 v131, v131
	v_rcp_f32_e32 v132, v132
	v_rcp_f32_e32 v133, v133
	v_pk_mul_f32 v[130:131], v[130:131], v[230:231] op_sel_hi:[1,0]
	v_pk_mul_f32 v[132:133], v[132:133], v[230:231] op_sel_hi:[1,0]
	v_pk_mul_f32 v[134:135], v[134:135], v[130:131]
	v_pk_mul_f32 v[136:137], v[136:137], v[132:133]
	v_cvt_pk_bf16_f32 v142, v134, v135
	v_cvt_pk_bf16_f32 v143, v136, v137
	v_mul_f32_e32 v130, v70, v229
	v_mul_f32_e32 v131, v71, v229
	v_mul_f32_e32 v132, v72, v229
	v_mul_f32_e32 v133, v73, v229
	v_exp_f32_e32 v130, v130
	v_exp_f32_e32 v131, v131
	v_exp_f32_e32 v132, v132
	v_exp_f32_e32 v133, v133
	v_pk_mul_f32 v[134:135], v[70:71], v[66:67]
	v_pk_mul_f32 v[136:137], v[72:73], v[68:69]
	v_add_f32_e32 v130, 1.0, v130
	v_add_f32_e32 v131, 1.0, v131
; DI unsigned pk2(float lo, float hi) { const f32x2v v = {lo, hi}; const bf16x2v b = __builtin_convertvector(v, bf16x2v); return __builtin_bit_cast(unsigned, b); }
; DI float siluf_(float x) { return x * sigmoidf_(x); }
; DI float rs_of(float ss, float inv_n) { return __builtin_amdgcn_rsqf(ss * inv_n + EPS); }
; DI float sum16_fq(const float* p, int fq) { const f32x4 a = *(const f32x4*)(p + 4 * fq); float s = (a[0] + a[1]) + (a[2] + a[3]); s += __shfl_xor(s, 16); s += __shfl_xor(s, 32); return s; }
; DI void epilogue(int kind, int l, const f32x4 (&acc)[2][2][4][2], const Unit& u, int wr, int wc, int fr, int fq) {
;     ...
;             for (int m = 0; m < 4; ++m) { const int row = row0 + ai * HALF + m * 16; const float rs = rs_of(sum16_fq(E.ss_in + (size_t)row * 16, fq), 1.f / 1024.f);
; #pragma unroll
;                 for (int bj = 0; bj < 2; ++bj) { const f32x4 g = acc[ai][bj][m][0] * rs, up = acc[ai][bj][m][1] * rs;
;                     u32x2 w; w.x = pk2(siluf_(g[0]) * up[0], siluf_(g[1]) * up[1]); w.y = pk2(siluf_(g[2]) * up[2], siluf_(g[3]) * up[3]);
;                     *(u32x2*)(E.o0 + (size_t)row * FF + ((col0 + bj * HALF) >> 1)) = w; } }
	v_add_f32_e32 v132, 1.0, v132
	v_add_f32_e32 v133, 1.0, v133
	v_rcp_f32_e32 v130, v130
	v_rcp_f32_e32 v131, v131
	v_rcp_f32_e32 v132, v132
	v_rcp_f32_e32 v133, v133
	v_pk_mul_f32 v[130:131], v[130:131], v[230:231] op_sel_hi:[1,0]
	v_pk_mul_f32 v[132:133], v[132:133], v[230:231] op_sel_hi:[1,0]
	v_pk_mul_f32 v[134:135], v[134:135], v[130:131]
	v_pk_mul_f32 v[136:137], v[136:137], v[132:133]
	v_cvt_pk_bf16_f32 v144, v134, v135
	v_cvt_pk_bf16_f32 v145, v136, v137
	s_nop 1
	v_permlane16_swap_b32_e32 v142, v144
	v_permlane16_swap_b32_e32 v143, v145
	global_store_dwordx4 v[150:151], v[142:145], off
	v_add_co_u32_e32 v150, vcc, 0x6e000, v150
	s_nop 1
	v_addc_co_u32_e32 v151, vcc, 0, v151, vcc
	v_mul_f32_e32 v130, v62, v233
	v_mul_f32_e32 v131, v63, v233
	v_mul_f32_e32 v132, v64, v233
	v_mul_f32_e32 v133, v65, v233
	v_exp_f32_e32 v130, v130
	v_exp_f32_e32 v131, v131
	v_exp_f32_e32 v132, v132
	v_exp_f32_e32 v133, v133
	v_pk_mul_f32 v[134:135], v[62:63], v[58:59]
	v_pk_mul_f32 v[136:137], v[64:65], v[60:61]
	v_add_f32_e32 v130, 1.0, v130
	v_add_f32_e32 v131, 1.0, v131
	v_add_f32_e32 v132, 1.0, v132
	v_add_f32_e32 v133, 1.0, v133
	v_rcp_f32_e32 v130, v130
	v_rcp_f32_e32 v131, v131
	v_rcp_f32_e32 v132, v132
	v_rcp_f32_e32 v133, v133
	v_pk_mul_f32 v[130:131], v[130:131], v[234:235] op_sel_hi:[1,0]
	v_pk_mul_f32 v[132:133], v[132:133], v[234:235] op_sel_hi:[1,0]
	v_pk_mul_f32 v[134:135], v[134:135], v[130:131]
	v_pk_mul_f32 v[136:137], v[136:137], v[132:133]
	v_cvt_pk_bf16_f32 v138, v134, v135
	v_cvt_pk_bf16_f32 v139, v136, v137
	v_mul_f32_e32 v130, v54, v233
	v_mul_f32_e32 v131, v55, v233
	v_mul_f32_e32 v132, v56, v233
	v_mul_f32_e32 v133, v57, v233
	v_exp_f32_e32 v130, v130
	v_exp_f32_e32 v131, v131
	v_exp_f32_e32 v132, v132
	v_exp_f32_e32 v133, v133
	v_pk_mul_f32 v[134:135], v[54:55], v[50:51]
	v_pk_mul_f32 v[136:137], v[56:57], v[52:53]
	v_add_f32_e32 v130, 1.0, v130
	v_add_f32_e32 v131, 1.0, v131
	v_add_f32_e32 v132, 1.0, v132
	v_add_f32_e32 v133, 1.0, v133
	v_rcp_f32_e32 v130, v130
	v_rcp_f32_e32 v131, v131
	v_rcp_f32_e32 v132, v132
	v_rcp_f32_e32 v133, v133
	v_pk_mul_f32 v[130:131], v[130:131], v[234:235] op_sel_hi:[1,0]
	v_pk_mul_f32 v[132:133], v[132:133], v[234:235] op_sel_hi:[1,0]
	v_pk_mul_f32 v[134:135], v[134:135], v[130:131]
	v_pk_mul_f32 v[136:137], v[136:137], v[132:133]
	v_cvt_pk_bf16_f32 v140, v134, v135
	v_cvt_pk_bf16_f32 v141, v136, v137
	s_nop 1
	v_permlane16_swap_b32_e32 v138, v140
	v_permlane16_swap_b32_e32 v139, v141
	global_store_dwordx4 v[150:151], v[138:141], off
	v_add_co_u32_e32 v150, vcc, 0x16000, v150
	s_nop 1
	v_addc_co_u32_e32 v151, vcc, 0, v151, vcc
	v_mul_f32_e32 v130, v46, v237
	v_mul_f32_e32 v131, v47, v237
	v_mul_f32_e32 v132, v48, v237
	v_mul_f32_e32 v133, v49, v237
	v_exp_f32_e32 v130, v130
	v_exp_f32_e32 v131, v131
	v_exp_f32_e32 v132, v132
	v_exp_f32_e32 v133, v133
	v_pk_mul_f32 v[134:135], v[46:47], v[42:43]
	v_pk_mul_f32 v[136:137], v[48:49], v[44:45]
	v_add_f32_e32 v130, 1.0, v130
	v_add_f32_e32 v131, 1.0, v131
	v_add_f32_e32 v132, 1.0, v132
	v_add_f32_e32 v133, 1.0, v133
	v_rcp_f32_e32 v130, v130
	v_rcp_f32_e32 v131, v131
	v_rcp_f32_e32 v132, v132
	v_rcp_f32_e32 v133, v133
	v_pk_mul_f32 v[130:131], v[130:131], v[238:239] op_sel_hi:[1,0]
	v_pk_mul_f32 v[132:133], v[132:133], v[238:239] op_sel_hi:[1,0]
	v_pk_mul_f32 v[134:135], v[134:135], v[130:131]
	v_pk_mul_f32 v[136:137], v[136:137], v[132:133]
	v_cvt_pk_bf16_f32 v142, v134, v135
	v_cvt_pk_bf16_f32 v143, v136, v137
	v_mul_f32_e32 v130, v38, v237
	v_mul_f32_e32 v131, v39, v237
	v_mul_f32_e32 v132, v40, v237
	v_mul_f32_e32 v133, v41, v237
	v_exp_f32_e32 v130, v130
	v_exp_f32_e32 v131, v131
	v_exp_f32_e32 v132, v132
	v_exp_f32_e32 v133, v133
	v_pk_mul_f32 v[134:135], v[38:39], v[34:35]
	v_pk_mul_f32 v[136:137], v[40:41], v[36:37]
	v_add_f32_e32 v130, 1.0, v130
	v_add_f32_e32 v131, 1.0, v131
	v_add_f32_e32 v132, 1.0, v132
	v_add_f32_e32 v133, 1.0, v133
	v_rcp_f32_e32 v130, v130
	v_rcp_f32_e32 v131, v131
	v_rcp_f32_e32 v132, v132
	v_rcp_f32_e32 v133, v133
	v_pk_mul_f32 v[130:131], v[130:131], v[238:239] op_sel_hi:[1,0]
	v_pk_mul_f32 v[132:133], v[132:133], v[238:239] op_sel_hi:[1,0]
; DI unsigned pk2(float lo, float hi) { const f32x2v v = {lo, hi}; const bf16x2v b = __builtin_convertvector(v, bf16x2v); return __builtin_bit_cast(unsigned, b); }
; DI float siluf_(float x) { return x * sigmoidf_(x); }
; DI float rs_of(float ss, float inv_n) { return __builtin_amdgcn_rsqf(ss * inv_n + EPS); }
; DI float sum16_fq(const float* p, int fq) { const f32x4 a = *(const f32x4*)(p + 4 * fq); float s = (a[0] + a[1]) + (a[2] + a[3]); s += __shfl_xor(s, 16); s += __shfl_xor(s, 32); return s; }
; DI void epilogue(int kind, int l, const f32x4 (&acc)[2][2][4][2], const Unit& u, int wr, int wc, int fr, int fq) {
;     ...
;             for (int m = 0; m < 4; ++m) { const int row = row0 + ai * HALF + m * 16; const float rs = rs_of(sum16_fq(E.ss_in + (size_t)row * 16, fq), 1.f / 1024.f);
; #pragma unroll
;                 for (int bj = 0; bj < 2; ++bj) { const f32x4 g = acc[ai][bj][m][0] * rs, up = acc[ai][bj][m][1] * rs;
;                     u32x2 w; w.x = pk2(siluf_(g[0]) * up[0], siluf_(g[1]) * up[1]); w.y = pk2(siluf_(g[2]) * up[2], siluf_(g[3]) * up[3]);
;                     *(u32x2*)(E.o0 + (size_t)row * FF + ((col0 + bj * HALF) >> 1)) = w; } }
	v_pk_mul_f32 v[134:135], v[134:135], v[130:131]
	v_pk_mul_f32 v[136:137], v[136:137], v[132:133]
	v_cvt_pk_bf16_f32 v144, v134, v135
	v_cvt_pk_bf16_f32 v145, v136, v137
	s_nop 1
	v_permlane16_swap_b32_e32 v142, v144
	v_permlane16_swap_b32_e32 v143, v145
	global_store_dwordx4 v[150:151], v[142:145], off
	v_add_co_u32_e32 v150, vcc, 0x16000, v150
	s_nop 1
	v_addc_co_u32_e32 v151, vcc, 0, v151, vcc
	v_mul_f32_e32 v130, v30, v241
	v_mul_f32_e32 v131, v31, v241
	v_mul_f32_e32 v132, v32, v241
	v_mul_f32_e32 v133, v33, v241
	v_exp_f32_e32 v130, v130
	v_exp_f32_e32 v131, v131
	v_exp_f32_e32 v132, v132
	v_exp_f32_e32 v133, v133
	v_pk_mul_f32 v[134:135], v[30:31], v[26:27]
	v_pk_mul_f32 v[136:137], v[32:33], v[28:29]
	v_add_f32_e32 v130, 1.0, v130
	v_add_f32_e32 v131, 1.0, v131
	v_add_f32_e32 v132, 1.0, v132
	v_add_f32_e32 v133, 1.0, v133
	v_rcp_f32_e32 v130, v130
	v_rcp_f32_e32 v131, v131
	v_rcp_f32_e32 v132, v132
	v_rcp_f32_e32 v133, v133
	v_pk_mul_f32 v[130:131], v[130:131], v[242:243] op_sel_hi:[1,0]
	v_pk_mul_f32 v[132:133], v[132:133], v[242:243] op_sel_hi:[1,0]
	v_pk_mul_f32 v[134:135], v[134:135], v[130:131]
	v_pk_mul_f32 v[136:137], v[136:137], v[132:133]
	v_cvt_pk_bf16_f32 v138, v134, v135
	v_cvt_pk_bf16_f32 v139, v136, v137
	v_mul_f32_e32 v130, v20, v241
	v_mul_f32_e32 v131, v21, v241
	v_mul_f32_e32 v132, v22, v241
	v_mul_f32_e32 v133, v23, v241
	v_exp_f32_e32 v130, v130
	v_exp_f32_e32 v131, v131
	v_exp_f32_e32 v132, v132
	v_exp_f32_e32 v133, v133
	v_pk_mul_f32 v[134:135], v[20:21], v[16:17]
	v_pk_mul_f32 v[136:137], v[22:23], v[18:19]
	v_add_f32_e32 v130, 1.0, v130
	v_add_f32_e32 v131, 1.0, v131
	v_add_f32_e32 v132, 1.0, v132
	v_add_f32_e32 v133, 1.0, v133
	v_rcp_f32_e32 v130, v130
	v_rcp_f32_e32 v131, v131
	v_rcp_f32_e32 v132, v132
	v_rcp_f32_e32 v133, v133
	v_pk_mul_f32 v[130:131], v[130:131], v[242:243] op_sel_hi:[1,0]
	v_pk_mul_f32 v[132:133], v[132:133], v[242:243] op_sel_hi:[1,0]
	v_pk_mul_f32 v[134:135], v[134:135], v[130:131]
	v_pk_mul_f32 v[136:137], v[136:137], v[132:133]
	v_cvt_pk_bf16_f32 v140, v134, v135
	v_cvt_pk_bf16_f32 v141, v136, v137
	s_nop 1
	v_permlane16_swap_b32_e32 v138, v140
	v_permlane16_swap_b32_e32 v139, v141
	global_store_dwordx4 v[150:151], v[138:141], off
	v_add_co_u32_e32 v150, vcc, 0x16000, v150
	s_nop 1
	v_addc_co_u32_e32 v151, vcc, 0, v151, vcc
	v_mul_f32_e32 v130, v12, v245
	v_mul_f32_e32 v131, v13, v245
	v_mul_f32_e32 v132, v14, v245
	v_mul_f32_e32 v133, v15, v245
	v_exp_f32_e32 v130, v130
	v_exp_f32_e32 v131, v131
	v_exp_f32_e32 v132, v132
	v_exp_f32_e32 v133, v133
	v_pk_mul_f32 v[134:135], v[12:13], v[8:9]
	v_pk_mul_f32 v[136:137], v[14:15], v[10:11]
	v_add_f32_e32 v130, 1.0, v130
	v_add_f32_e32 v131, 1.0, v131
	v_add_f32_e32 v132, 1.0, v132
	v_add_f32_e32 v133, 1.0, v133
	v_rcp_f32_e32 v130, v130
	v_rcp_f32_e32 v131, v131
	v_rcp_f32_e32 v132, v132
	v_rcp_f32_e32 v133, v133
	v_pk_mul_f32 v[130:131], v[130:131], v[246:247] op_sel_hi:[1,0]
	v_pk_mul_f32 v[132:133], v[132:133], v[246:247] op_sel_hi:[1,0]
	v_pk_mul_f32 v[134:135], v[134:135], v[130:131]
	v_pk_mul_f32 v[136:137], v[136:137], v[132:133]
	v_cvt_pk_bf16_f32 v142, v134, v135
	v_cvt_pk_bf16_f32 v143, v136, v137
	v_mul_f32_e32 v130, v4, v245
	v_mul_f32_e32 v131, v5, v245
	v_mul_f32_e32 v132, v6, v245
	v_mul_f32_e32 v133, v7, v245
	v_exp_f32_e32 v130, v130
	v_exp_f32_e32 v131, v131
	v_exp_f32_e32 v132, v132
	v_exp_f32_e32 v133, v133
	v_pk_mul_f32 v[134:135], v[4:5], v[0:1]
	v_pk_mul_f32 v[136:137], v[6:7], v[2:3]
	v_add_f32_e32 v130, 1.0, v130
	v_add_f32_e32 v131, 1.0, v131
	v_add_f32_e32 v132, 1.0, v132
	v_add_f32_e32 v133, 1.0, v133
	v_rcp_f32_e32 v130, v130
	v_rcp_f32_e32 v131, v131
	v_rcp_f32_e32 v132, v132
	v_rcp_f32_e32 v133, v133
	v_pk_mul_f32 v[130:131], v[130:131], v[246:247] op_sel_hi:[1,0]
	v_pk_mul_f32 v[132:133], v[132:133], v[246:247] op_sel_hi:[1,0]
	v_pk_mul_f32 v[134:135], v[134:135], v[130:131]
	v_pk_mul_f32 v[136:137], v[136:137], v[132:133]
	v_cvt_pk_bf16_f32 v144, v134, v135
	v_cvt_pk_bf16_f32 v145, v136, v137
	s_nop 1
	v_permlane16_swap_b32_e32 v142, v144
	v_permlane16_swap_b32_e32 v143, v145
	global_store_dwordx4 v[150:151], v[142:145], off
